# UP epilogue: tap weights read from LDS once per column group and used for both row halves (16 fewer LDS reads per wave per tile)
# speedup vs baseline: 1.0004x; 1.0004x over previous
.Lnepia_j0:
	s_waitcnt lgkmcnt(0)
	ds_read_b128 v[162:165], v227 offset:4608
	ds_read_b128 v[166:169], v227 offset:5632
	v_mov_b32_dpp v118, v78 row_shr:1 row_mask:0xf bank_mask:0xf
	v_mov_b32_dpp v122, v138 row_shr:1 row_mask:0xf bank_mask:0xf
	v_mov_b32_dpp v119, v79 row_shr:1 row_mask:0xf bank_mask:0xf
	v_mov_b32_dpp v123, v139 row_shr:1 row_mask:0xf bank_mask:0xf
	v_mov_b32_dpp v120, v80 row_shr:1 row_mask:0xf bank_mask:0xf
	v_mov_b32_dpp v124, v140 row_shr:1 row_mask:0xf bank_mask:0xf
	v_mov_b32_dpp v121, v81 row_shr:1 row_mask:0xf bank_mask:0xf
	v_mov_b32_dpp v125, v141 row_shr:1 row_mask:0xf bank_mask:0xf
	v_pk_fma_f32 v[138:139], v[202:203], v[138:139], v[206:207]
	v_pk_fma_f32 v[140:141], v[204:205], v[140:141], v[208:209]
	v_pk_fma_f32 v[138:139], v[198:199], v[78:79], v[138:139]
	v_pk_fma_f32 v[140:141], v[200:201], v[80:81], v[140:141]
	v_pk_fma_f32 v[138:139], v[194:195], v[130:131], v[138:139]
	v_pk_fma_f32 v[140:141], v[196:197], v[132:133], v[140:141]
	v_pk_fma_f32 v[78:79], v[202:203], v[78:79], v[206:207]
	v_pk_fma_f32 v[80:81], v[204:205], v[80:81], v[208:209]
	v_pk_fma_f32 v[78:79], v[198:199], v[130:131], v[78:79]
	v_pk_fma_f32 v[80:81], v[200:201], v[132:133], v[80:81]
	v_pk_fma_f32 v[78:79], v[194:195], v[134:135], v[78:79]
	v_pk_fma_f32 v[80:81], v[196:197], v[136:137], v[80:81]
	v_pk_fma_f32 v[130:131], v[202:203], v[130:131], v[206:207]
	v_pk_fma_f32 v[132:133], v[204:205], v[132:133], v[208:209]
	v_pk_fma_f32 v[130:131], v[198:199], v[134:135], v[130:131]
	v_pk_fma_f32 v[132:133], v[200:201], v[136:137], v[132:133]
	v_pk_fma_f32 v[130:131], v[194:195], v[122:123], v[130:131]
	v_pk_fma_f32 v[132:133], v[196:197], v[124:125], v[132:133]
	v_pk_fma_f32 v[134:135], v[202:203], v[134:135], v[206:207]
	v_pk_fma_f32 v[136:137], v[204:205], v[136:137], v[208:209]
	v_pk_fma_f32 v[134:135], v[198:199], v[122:123], v[134:135]
	v_pk_fma_f32 v[136:137], v[200:201], v[124:125], v[136:137]
	v_pk_fma_f32 v[134:135], v[194:195], v[118:119], v[134:135]
	v_pk_fma_f32 v[136:137], v[196:197], v[120:121], v[136:137]
	s_cmp_lg_u32 s50, 0
	s_cbranch_scc1 .Lnepia_np0
	v_cmp_eq_u32_e32 vcc, 0, v224
	s_and_saveexec_b64 s[8:9], vcc
	s_add_u32 s48, s88, 0x2d00000
	s_addc_u32 s49, s89, 0
	global_store_dwordx4 v229, v[134:137], s[48:49] offset:0
	global_store_dwordx4 v231, v[130:133], s[48:49] offset:0
	s_or_b64 exec, exec, s[8:9]
	s_nop 1
.Lnepia_np0:
	s_waitcnt lgkmcnt(0)
	ds_read_b128 v[146:149], v226 offset:0
	ds_read_b128 v[150:153], v226 offset:1024
	ds_read_b128 v[154:157], v226 offset:2048
	ds_read_b128 v[158:161], v226 offset:3072
	s_cmp_eq_u32 s50, 0
	s_cbranch_scc1 .Lnepia_z2
	ds_read_b128 v[118:121], v227 offset:0
	ds_read_b128 v[122:125], v227 offset:1024
	s_branch .Lnepia_j2

.Lnepia_j2:
	v_mov_b32_dpp v162, v102 row_shr:1 row_mask:0xf bank_mask:0xf
	v_mov_b32_dpp v166, v126 row_shr:1 row_mask:0xf bank_mask:0xf
	v_mov_b32_dpp v163, v103 row_shr:1 row_mask:0xf bank_mask:0xf
	v_mov_b32_dpp v167, v127 row_shr:1 row_mask:0xf bank_mask:0xf
	v_mov_b32_dpp v164, v104 row_shr:1 row_mask:0xf bank_mask:0xf
	v_mov_b32_dpp v168, v128 row_shr:1 row_mask:0xf bank_mask:0xf
	v_mov_b32_dpp v165, v105 row_shr:1 row_mask:0xf bank_mask:0xf
	v_mov_b32_dpp v169, v129 row_shr:1 row_mask:0xf bank_mask:0xf
	v_pk_fma_f32 v[126:127], v[202:203], v[126:127], v[206:207]
	v_pk_fma_f32 v[128:129], v[204:205], v[128:129], v[208:209]
	v_pk_fma_f32 v[126:127], v[198:199], v[102:103], v[126:127]
	v_pk_fma_f32 v[128:129], v[200:201], v[104:105], v[128:129]
	v_pk_fma_f32 v[126:127], v[194:195], v[106:107], v[126:127]
	v_pk_fma_f32 v[128:129], v[196:197], v[108:109], v[128:129]
	v_pk_fma_f32 v[102:103], v[202:203], v[102:103], v[206:207]
	v_pk_fma_f32 v[104:105], v[204:205], v[104:105], v[208:209]
	v_pk_fma_f32 v[102:103], v[198:199], v[106:107], v[102:103]
	v_pk_fma_f32 v[104:105], v[200:201], v[108:109], v[104:105]
	v_pk_fma_f32 v[102:103], v[194:195], v[110:111], v[102:103]
	v_pk_fma_f32 v[104:105], v[196:197], v[112:113], v[104:105]
	v_pk_fma_f32 v[106:107], v[202:203], v[106:107], v[206:207]
	v_pk_fma_f32 v[108:109], v[204:205], v[108:109], v[208:209]
	v_pk_fma_f32 v[106:107], v[198:199], v[110:111], v[106:107]
	v_pk_fma_f32 v[108:109], v[200:201], v[112:113], v[108:109]
	v_pk_fma_f32 v[106:107], v[194:195], v[166:167], v[106:107]
	v_pk_fma_f32 v[108:109], v[196:197], v[168:169], v[108:109]
	v_pk_fma_f32 v[110:111], v[202:203], v[110:111], v[206:207]
	v_pk_fma_f32 v[112:113], v[204:205], v[112:113], v[208:209]
	v_pk_fma_f32 v[110:111], v[198:199], v[166:167], v[110:111]
	v_pk_fma_f32 v[112:113], v[200:201], v[168:169], v[112:113]
	v_pk_fma_f32 v[110:111], v[194:195], v[162:163], v[110:111]
	v_pk_fma_f32 v[112:113], v[196:197], v[164:165], v[112:113]
	s_waitcnt lgkmcnt(0)
	ds_read_b128 v[162:165], v227 offset:4096
	ds_read_b128 v[166:169], v227 offset:5120
	v_mov_b32_dpp v118, v46 row_shr:1 row_mask:0xf bank_mask:0xf
	v_mov_b32_dpp v122, v142 row_shr:1 row_mask:0xf bank_mask:0xf
	v_mov_b32_dpp v119, v47 row_shr:1 row_mask:0xf bank_mask:0xf
	v_mov_b32_dpp v123, v143 row_shr:1 row_mask:0xf bank_mask:0xf
	v_mov_b32_dpp v120, v48 row_shr:1 row_mask:0xf bank_mask:0xf
	v_mov_b32_dpp v124, v144 row_shr:1 row_mask:0xf bank_mask:0xf
	v_mov_b32_dpp v121, v49 row_shr:1 row_mask:0xf bank_mask:0xf
	v_mov_b32_dpp v125, v145 row_shr:1 row_mask:0xf bank_mask:0xf
	v_pk_fma_f32 v[142:143], v[154:155], v[142:143], v[158:159]
	v_pk_fma_f32 v[144:145], v[156:157], v[144:145], v[160:161]
	v_pk_fma_f32 v[142:143], v[150:151], v[46:47], v[142:143]
	v_pk_fma_f32 v[144:145], v[152:153], v[48:49], v[144:145]
	v_pk_fma_f32 v[142:143], v[146:147], v[50:51], v[142:143]
	v_pk_fma_f32 v[144:145], v[148:149], v[52:53], v[144:145]
	v_pk_fma_f32 v[46:47], v[154:155], v[46:47], v[158:159]
	v_pk_fma_f32 v[48:49], v[156:157], v[48:49], v[160:161]
	v_pk_fma_f32 v[46:47], v[150:151], v[50:51], v[46:47]
	v_pk_fma_f32 v[48:49], v[152:153], v[52:53], v[48:49]
	v_pk_fma_f32 v[46:47], v[146:147], v[62:63], v[46:47]
	v_pk_fma_f32 v[48:49], v[148:149], v[64:65], v[48:49]
	v_pk_fma_f32 v[50:51], v[154:155], v[50:51], v[158:159]
	v_pk_fma_f32 v[52:53], v[156:157], v[52:53], v[160:161]
	v_pk_fma_f32 v[50:51], v[150:151], v[62:63], v[50:51]
	v_pk_fma_f32 v[52:53], v[152:153], v[64:65], v[52:53]
	v_pk_fma_f32 v[50:51], v[146:147], v[122:123], v[50:51]
	v_pk_fma_f32 v[52:53], v[148:149], v[124:125], v[52:53]
	v_pk_fma_f32 v[62:63], v[154:155], v[62:63], v[158:159]
	v_pk_fma_f32 v[64:65], v[156:157], v[64:65], v[160:161]
	v_pk_fma_f32 v[62:63], v[150:151], v[122:123], v[62:63]
	v_pk_fma_f32 v[64:65], v[152:153], v[124:125], v[64:65]
	v_pk_fma_f32 v[62:63], v[146:147], v[118:119], v[62:63]
	v_pk_fma_f32 v[64:65], v[148:149], v[120:121], v[64:65]
	s_cmp_lg_u32 s50, 0
	s_cbranch_scc1 .Lnepia_np2
	v_cmp_eq_u32_e32 vcc, 0, v224
	s_and_saveexec_b64 s[8:9], vcc
	s_add_u32 s48, s88, 0x2d00000
	s_addc_u32 s49, s89, 0
	global_store_dwordx4 v228, v[62:65], s[48:49] offset:0
	global_store_dwordx4 v230, v[50:53], s[48:49] offset:0
	s_or_b64 exec, exec, s[8:9]
	s_nop 1
.Lnepia_np2:
	v_pk_mul_f32 v[30:31], v[62:63], s[100:101]
	v_pk_mul_f32 v[32:33], v[64:65], s[100:101]
	v_pk_mul_f32 v[54:55], v[50:51], s[100:101]
	v_pk_mul_f32 v[56:57], v[52:53], s[100:101]
	v_exp_f32_e32 v30, v30
	v_exp_f32_e32 v31, v31
	v_exp_f32_e32 v32, v32
	v_exp_f32_e32 v33, v33
	v_exp_f32_e32 v54, v54
	v_exp_f32_e32 v55, v55
	v_exp_f32_e32 v56, v56
	v_exp_f32_e32 v57, v57
	v_pk_add_f32 v[30:31], v[30:31], s[98:99]
	v_pk_add_f32 v[32:33], v[32:33], s[98:99]
	v_pk_add_f32 v[54:55], v[54:55], s[98:99]
	v_pk_add_f32 v[56:57], v[56:57], s[98:99]
	v_rcp_f32_e32 v30, v30
	v_rcp_f32_e32 v31, v31
	v_rcp_f32_e32 v32, v32
	v_rcp_f32_e32 v33, v33
	v_rcp_f32_e32 v54, v54
	v_rcp_f32_e32 v55, v55
	v_rcp_f32_e32 v56, v56
	v_rcp_f32_e32 v57, v57
	v_pk_mul_f32 v[62:63], v[62:63], v[134:135]
	v_pk_mul_f32 v[64:65], v[64:65], v[136:137]
	v_pk_mul_f32 v[50:51], v[50:51], v[130:131]
	v_pk_mul_f32 v[52:53], v[52:53], v[132:133]
	v_pk_mul_f32 v[62:63], v[62:63], v[30:31]
	v_pk_mul_f32 v[64:65], v[64:65], v[32:33]
	v_pk_mul_f32 v[50:51], v[50:51], v[54:55]
	v_pk_mul_f32 v[52:53], v[52:53], v[56:57]
	v_pk_mul_f32 v[30:31], v[46:47], s[100:101]
	v_pk_mul_f32 v[32:33], v[48:49], s[100:101]
	v_pk_mul_f32 v[54:55], v[142:143], s[100:101]
	v_pk_mul_f32 v[56:57], v[144:145], s[100:101]
	v_exp_f32_e32 v30, v30
	v_exp_f32_e32 v31, v31
	v_exp_f32_e32 v32, v32
	v_exp_f32_e32 v33, v33
	v_exp_f32_e32 v54, v54
	v_exp_f32_e32 v55, v55
	v_exp_f32_e32 v56, v56
	v_exp_f32_e32 v57, v57
	v_pk_add_f32 v[30:31], v[30:31], s[98:99]
	v_pk_add_f32 v[32:33], v[32:33], s[98:99]
	v_pk_add_f32 v[54:55], v[54:55], s[98:99]
	v_pk_add_f32 v[56:57], v[56:57], s[98:99]
	v_rcp_f32_e32 v30, v30
	v_rcp_f32_e32 v31, v31
	v_rcp_f32_e32 v32, v32
	v_rcp_f32_e32 v33, v33
	v_rcp_f32_e32 v54, v54
	v_rcp_f32_e32 v55, v55
	v_rcp_f32_e32 v56, v56
	v_rcp_f32_e32 v57, v57
	v_pk_mul_f32 v[46:47], v[46:47], v[78:79]
	v_pk_mul_f32 v[48:49], v[48:49], v[80:81]
	v_pk_mul_f32 v[142:143], v[142:143], v[138:139]
	v_pk_mul_f32 v[144:145], v[144:145], v[140:141]
	v_pk_mul_f32 v[46:47], v[46:47], v[30:31]
	v_pk_mul_f32 v[48:49], v[48:49], v[32:33]
	v_pk_mul_f32 v[142:143], v[142:143], v[54:55]
	v_pk_mul_f32 v[144:145], v[144:145], v[56:57]
	s_waitcnt lgkmcnt(0)
	ds_read_b128 v[194:197], v226 offset:528
	ds_read_b128 v[198:201], v226 offset:1552
	ds_read_b128 v[202:205], v226 offset:2576
	ds_read_b128 v[206:209], v226 offset:3600
	s_cmp_eq_u32 s50, 0
	s_cbranch_scc1 .Lnepia_z4
	ds_read_b128 v[118:121], v227 offset:528
	ds_read_b128 v[122:125], v227 offset:1552
	s_branch .Lnepia_j4

.Lnepia_j4:
	v_mov_b32_dpp v162, v86 row_shr:1 row_mask:0xf bank_mask:0xf
	v_mov_b32_dpp v166, v114 row_shr:1 row_mask:0xf bank_mask:0xf
	v_mov_b32_dpp v163, v87 row_shr:1 row_mask:0xf bank_mask:0xf
	v_mov_b32_dpp v167, v115 row_shr:1 row_mask:0xf bank_mask:0xf
	v_mov_b32_dpp v164, v88 row_shr:1 row_mask:0xf bank_mask:0xf
	v_mov_b32_dpp v168, v116 row_shr:1 row_mask:0xf bank_mask:0xf
	v_mov_b32_dpp v165, v89 row_shr:1 row_mask:0xf bank_mask:0xf
	v_mov_b32_dpp v169, v117 row_shr:1 row_mask:0xf bank_mask:0xf
	v_pk_fma_f32 v[114:115], v[154:155], v[114:115], v[158:159]
	v_pk_fma_f32 v[116:117], v[156:157], v[116:117], v[160:161]
	v_pk_fma_f32 v[114:115], v[150:151], v[86:87], v[114:115]
	v_pk_fma_f32 v[116:117], v[152:153], v[88:89], v[116:117]
	v_pk_fma_f32 v[114:115], v[146:147], v[90:91], v[114:115]
	v_pk_fma_f32 v[116:117], v[148:149], v[92:93], v[116:117]
	v_pk_fma_f32 v[86:87], v[154:155], v[86:87], v[158:159]
	v_pk_fma_f32 v[88:89], v[156:157], v[88:89], v[160:161]
	v_pk_fma_f32 v[86:87], v[150:151], v[90:91], v[86:87]
	v_pk_fma_f32 v[88:89], v[152:153], v[92:93], v[88:89]
	v_pk_fma_f32 v[86:87], v[146:147], v[94:95], v[86:87]
	v_pk_fma_f32 v[88:89], v[148:149], v[96:97], v[88:89]
	v_pk_fma_f32 v[90:91], v[154:155], v[90:91], v[158:159]
	v_pk_fma_f32 v[92:93], v[156:157], v[92:93], v[160:161]
	v_pk_fma_f32 v[90:91], v[150:151], v[94:95], v[90:91]
	v_pk_fma_f32 v[92:93], v[152:153], v[96:97], v[92:93]
	v_pk_fma_f32 v[90:91], v[146:147], v[166:167], v[90:91]
	v_pk_fma_f32 v[92:93], v[148:149], v[168:169], v[92:93]
	v_pk_fma_f32 v[94:95], v[154:155], v[94:95], v[158:159]
	v_pk_fma_f32 v[96:97], v[156:157], v[96:97], v[160:161]
	v_pk_fma_f32 v[94:95], v[150:151], v[166:167], v[94:95]
	v_pk_fma_f32 v[96:97], v[152:153], v[168:169], v[96:97]
	v_pk_fma_f32 v[94:95], v[146:147], v[162:163], v[94:95]
	v_pk_fma_f32 v[96:97], v[148:149], v[164:165], v[96:97]
	v_pk_mul_f32 v[30:31], v[94:95], s[100:101]
	v_pk_mul_f32 v[32:33], v[96:97], s[100:101]
	v_pk_mul_f32 v[54:55], v[90:91], s[100:101]
	v_pk_mul_f32 v[56:57], v[92:93], s[100:101]
	v_exp_f32_e32 v30, v30
	v_exp_f32_e32 v31, v31
	v_exp_f32_e32 v32, v32
	v_exp_f32_e32 v33, v33
	v_exp_f32_e32 v54, v54
	v_exp_f32_e32 v55, v55
	v_exp_f32_e32 v56, v56
	v_exp_f32_e32 v57, v57
	v_pk_add_f32 v[30:31], v[30:31], s[98:99]
	v_pk_add_f32 v[32:33], v[32:33], s[98:99]
	v_pk_add_f32 v[54:55], v[54:55], s[98:99]
	v_pk_add_f32 v[56:57], v[56:57], s[98:99]
	v_rcp_f32_e32 v30, v30
	v_rcp_f32_e32 v31, v31
	v_rcp_f32_e32 v32, v32
	v_rcp_f32_e32 v33, v33
	v_rcp_f32_e32 v54, v54
	v_rcp_f32_e32 v55, v55
	v_rcp_f32_e32 v56, v56
	v_rcp_f32_e32 v57, v57
	v_pk_mul_f32 v[94:95], v[94:95], v[110:111]
	v_pk_mul_f32 v[96:97], v[96:97], v[112:113]
	v_pk_mul_f32 v[90:91], v[90:91], v[106:107]
	v_pk_mul_f32 v[92:93], v[92:93], v[108:109]
	v_pk_mul_f32 v[94:95], v[94:95], v[30:31]
	v_pk_mul_f32 v[96:97], v[96:97], v[32:33]
	v_pk_mul_f32 v[90:91], v[90:91], v[54:55]
	v_pk_mul_f32 v[92:93], v[92:93], v[56:57]
	v_pk_mul_f32 v[30:31], v[86:87], s[100:101]
	v_pk_mul_f32 v[32:33], v[88:89], s[100:101]
	v_pk_mul_f32 v[54:55], v[114:115], s[100:101]
	v_pk_mul_f32 v[56:57], v[116:117], s[100:101]
	v_exp_f32_e32 v30, v30
	v_exp_f32_e32 v31, v31
	v_exp_f32_e32 v32, v32
	v_exp_f32_e32 v33, v33
	v_exp_f32_e32 v54, v54
	v_exp_f32_e32 v55, v55
	v_exp_f32_e32 v56, v56
	v_exp_f32_e32 v57, v57
	v_pk_add_f32 v[30:31], v[30:31], s[98:99]
	v_pk_add_f32 v[32:33], v[32:33], s[98:99]
	v_pk_add_f32 v[54:55], v[54:55], s[98:99]
	v_pk_add_f32 v[56:57], v[56:57], s[98:99]
	v_rcp_f32_e32 v30, v30
	v_rcp_f32_e32 v31, v31
	v_rcp_f32_e32 v32, v32
	v_rcp_f32_e32 v33, v33
	v_rcp_f32_e32 v54, v54
	v_rcp_f32_e32 v55, v55
	v_rcp_f32_e32 v56, v56
	v_rcp_f32_e32 v57, v57
	v_pk_mul_f32 v[86:87], v[86:87], v[102:103]
	v_pk_mul_f32 v[88:89], v[88:89], v[104:105]
	v_pk_mul_f32 v[114:115], v[114:115], v[126:127]
	v_pk_mul_f32 v[116:117], v[116:117], v[128:129]
	v_pk_mul_f32 v[86:87], v[86:87], v[30:31]
	v_pk_mul_f32 v[88:89], v[88:89], v[32:33]
	v_pk_mul_f32 v[114:115], v[114:115], v[54:55]
	v_pk_mul_f32 v[116:117], v[116:117], v[56:57]
	s_waitcnt lgkmcnt(0)
	ds_read_b128 v[162:165], v227 offset:4624
	ds_read_b128 v[166:169], v227 offset:5648
	v_mov_b32_dpp v118, v66 row_shr:1 row_mask:0xf bank_mask:0xf
	v_mov_b32_dpp v122, v98 row_shr:1 row_mask:0xf bank_mask:0xf
	v_mov_b32_dpp v119, v67 row_shr:1 row_mask:0xf bank_mask:0xf
	v_mov_b32_dpp v123, v99 row_shr:1 row_mask:0xf bank_mask:0xf
	v_mov_b32_dpp v120, v68 row_shr:1 row_mask:0xf bank_mask:0xf
	v_mov_b32_dpp v124, v100 row_shr:1 row_mask:0xf bank_mask:0xf
	v_mov_b32_dpp v121, v69 row_shr:1 row_mask:0xf bank_mask:0xf
	v_mov_b32_dpp v125, v101 row_shr:1 row_mask:0xf bank_mask:0xf
	v_pk_fma_f32 v[98:99], v[202:203], v[98:99], v[206:207]
	v_pk_fma_f32 v[100:101], v[204:205], v[100:101], v[208:209]
	v_pk_fma_f32 v[98:99], v[198:199], v[66:67], v[98:99]
	v_pk_fma_f32 v[100:101], v[200:201], v[68:69], v[100:101]
	v_pk_fma_f32 v[98:99], v[194:195], v[70:71], v[98:99]
	v_pk_fma_f32 v[100:101], v[196:197], v[72:73], v[100:101]
	v_pk_fma_f32 v[66:67], v[202:203], v[66:67], v[206:207]
	v_pk_fma_f32 v[68:69], v[204:205], v[68:69], v[208:209]
	v_pk_fma_f32 v[66:67], v[198:199], v[70:71], v[66:67]
	v_pk_fma_f32 v[68:69], v[200:201], v[72:73], v[68:69]
	v_pk_fma_f32 v[66:67], v[194:195], v[74:75], v[66:67]
	v_pk_fma_f32 v[68:69], v[196:197], v[76:77], v[68:69]
	v_pk_fma_f32 v[70:71], v[202:203], v[70:71], v[206:207]
	v_pk_fma_f32 v[72:73], v[204:205], v[72:73], v[208:209]
	v_pk_fma_f32 v[70:71], v[198:199], v[74:75], v[70:71]
	v_pk_fma_f32 v[72:73], v[200:201], v[76:77], v[72:73]
	v_pk_fma_f32 v[70:71], v[194:195], v[122:123], v[70:71]
	v_pk_fma_f32 v[72:73], v[196:197], v[124:125], v[72:73]
	v_pk_fma_f32 v[74:75], v[202:203], v[74:75], v[206:207]
	v_pk_fma_f32 v[76:77], v[204:205], v[76:77], v[208:209]
	v_pk_fma_f32 v[74:75], v[198:199], v[122:123], v[74:75]
	v_pk_fma_f32 v[76:77], v[200:201], v[124:125], v[76:77]
	v_pk_fma_f32 v[74:75], v[194:195], v[118:119], v[74:75]
	v_pk_fma_f32 v[76:77], v[196:197], v[120:121], v[76:77]
	s_cmp_lg_u32 s50, 0
	s_cbranch_scc1 .Lnepia_np4
	v_cmp_eq_u32_e32 vcc, 0, v224
	s_and_saveexec_b64 s[8:9], vcc
	s_add_u32 s48, s88, 0x2d00000
	s_addc_u32 s49, s89, 0
	global_store_dwordx4 v229, v[74:77], s[48:49] offset:16
	global_store_dwordx4 v231, v[70:73], s[48:49] offset:16
	s_or_b64 exec, exec, s[8:9]
	s_nop 1
.Lnepia_np4:
	s_waitcnt lgkmcnt(0)
	ds_read_b128 v[146:149], v226 offset:16
	ds_read_b128 v[150:153], v226 offset:1040
	ds_read_b128 v[154:157], v226 offset:2064
	ds_read_b128 v[158:161], v226 offset:3088
	s_cmp_eq_u32 s50, 0
	s_cbranch_scc1 .Lnepia_z6
	ds_read_b128 v[118:121], v227 offset:16
	ds_read_b128 v[122:125], v227 offset:1040
	s_branch .Lnepia_j6

.Lnepia_j6:
	v_mov_b32_dpp v162, v14 row_shr:1 row_mask:0xf bank_mask:0xf
	v_mov_b32_dpp v166, v58 row_shr:1 row_mask:0xf bank_mask:0xf
	v_mov_b32_dpp v163, v15 row_shr:1 row_mask:0xf bank_mask:0xf
	v_mov_b32_dpp v167, v59 row_shr:1 row_mask:0xf bank_mask:0xf
	v_mov_b32_dpp v164, v16 row_shr:1 row_mask:0xf bank_mask:0xf
	v_mov_b32_dpp v168, v60 row_shr:1 row_mask:0xf bank_mask:0xf
	v_mov_b32_dpp v165, v17 row_shr:1 row_mask:0xf bank_mask:0xf
	v_mov_b32_dpp v169, v61 row_shr:1 row_mask:0xf bank_mask:0xf
	v_pk_fma_f32 v[58:59], v[202:203], v[58:59], v[206:207]
	v_pk_fma_f32 v[60:61], v[204:205], v[60:61], v[208:209]
	v_pk_fma_f32 v[58:59], v[198:199], v[14:15], v[58:59]
	v_pk_fma_f32 v[60:61], v[200:201], v[16:17], v[60:61]
	v_pk_fma_f32 v[58:59], v[194:195], v[18:19], v[58:59]
	v_pk_fma_f32 v[60:61], v[196:197], v[20:21], v[60:61]
	v_pk_fma_f32 v[14:15], v[202:203], v[14:15], v[206:207]
	v_pk_fma_f32 v[16:17], v[204:205], v[16:17], v[208:209]
	v_pk_fma_f32 v[14:15], v[198:199], v[18:19], v[14:15]
	v_pk_fma_f32 v[16:17], v[200:201], v[20:21], v[16:17]
	v_pk_fma_f32 v[14:15], v[194:195], v[22:23], v[14:15]
	v_pk_fma_f32 v[16:17], v[196:197], v[24:25], v[16:17]
	v_pk_fma_f32 v[18:19], v[202:203], v[18:19], v[206:207]
	v_pk_fma_f32 v[20:21], v[204:205], v[20:21], v[208:209]
	v_pk_fma_f32 v[18:19], v[198:199], v[22:23], v[18:19]
	v_pk_fma_f32 v[20:21], v[200:201], v[24:25], v[20:21]
	v_pk_fma_f32 v[18:19], v[194:195], v[166:167], v[18:19]
	v_pk_fma_f32 v[20:21], v[196:197], v[168:169], v[20:21]
	v_pk_fma_f32 v[22:23], v[202:203], v[22:23], v[206:207]
	v_pk_fma_f32 v[24:25], v[204:205], v[24:25], v[208:209]
	v_pk_fma_f32 v[22:23], v[198:199], v[166:167], v[22:23]
	v_pk_fma_f32 v[24:25], v[200:201], v[168:169], v[24:25]
	v_pk_fma_f32 v[22:23], v[194:195], v[162:163], v[22:23]
	v_pk_fma_f32 v[24:25], v[196:197], v[164:165], v[24:25]
	s_waitcnt lgkmcnt(0)
	ds_read_b128 v[162:165], v227 offset:4112
	ds_read_b128 v[166:169], v227 offset:5136
	v_mov_b32_dpp v118, v34 row_shr:1 row_mask:0xf bank_mask:0xf
	v_mov_b32_dpp v122, v82 row_shr:1 row_mask:0xf bank_mask:0xf
	v_mov_b32_dpp v119, v35 row_shr:1 row_mask:0xf bank_mask:0xf
	v_mov_b32_dpp v123, v83 row_shr:1 row_mask:0xf bank_mask:0xf
	v_mov_b32_dpp v120, v36 row_shr:1 row_mask:0xf bank_mask:0xf
	v_mov_b32_dpp v124, v84 row_shr:1 row_mask:0xf bank_mask:0xf
	v_mov_b32_dpp v121, v37 row_shr:1 row_mask:0xf bank_mask:0xf
	v_mov_b32_dpp v125, v85 row_shr:1 row_mask:0xf bank_mask:0xf
	v_pk_fma_f32 v[82:83], v[154:155], v[82:83], v[158:159]
	v_pk_fma_f32 v[84:85], v[156:157], v[84:85], v[160:161]
	v_pk_fma_f32 v[82:83], v[150:151], v[34:35], v[82:83]
	v_pk_fma_f32 v[84:85], v[152:153], v[36:37], v[84:85]
	v_pk_fma_f32 v[82:83], v[146:147], v[38:39], v[82:83]
	v_pk_fma_f32 v[84:85], v[148:149], v[40:41], v[84:85]
	v_pk_fma_f32 v[34:35], v[154:155], v[34:35], v[158:159]
	v_pk_fma_f32 v[36:37], v[156:157], v[36:37], v[160:161]
	v_pk_fma_f32 v[34:35], v[150:151], v[38:39], v[34:35]
	v_pk_fma_f32 v[36:37], v[152:153], v[40:41], v[36:37]
	v_pk_fma_f32 v[34:35], v[146:147], v[42:43], v[34:35]
	v_pk_fma_f32 v[36:37], v[148:149], v[44:45], v[36:37]
	v_pk_fma_f32 v[38:39], v[154:155], v[38:39], v[158:159]
	v_pk_fma_f32 v[40:41], v[156:157], v[40:41], v[160:161]
	v_pk_fma_f32 v[38:39], v[150:151], v[42:43], v[38:39]
	v_pk_fma_f32 v[40:41], v[152:153], v[44:45], v[40:41]
	v_pk_fma_f32 v[38:39], v[146:147], v[122:123], v[38:39]
	v_pk_fma_f32 v[40:41], v[148:149], v[124:125], v[40:41]
	v_pk_fma_f32 v[42:43], v[154:155], v[42:43], v[158:159]
	v_pk_fma_f32 v[44:45], v[156:157], v[44:45], v[160:161]
	v_pk_fma_f32 v[42:43], v[150:151], v[122:123], v[42:43]
	v_pk_fma_f32 v[44:45], v[152:153], v[124:125], v[44:45]
	v_pk_fma_f32 v[42:43], v[146:147], v[118:119], v[42:43]
	v_pk_fma_f32 v[44:45], v[148:149], v[120:121], v[44:45]
	s_cmp_lg_u32 s50, 0
	s_cbranch_scc1 .Lnepia_np6
	v_cmp_eq_u32_e32 vcc, 0, v224
	s_and_saveexec_b64 s[8:9], vcc
	s_add_u32 s48, s88, 0x2d00000
	s_addc_u32 s49, s89, 0
	global_store_dwordx4 v228, v[42:45], s[48:49] offset:16
	global_store_dwordx4 v230, v[38:41], s[48:49] offset:16
	s_or_b64 exec, exec, s[8:9]
	s_nop 1
.Lnepia_np6:
	v_pk_mul_f32 v[30:31], v[42:43], s[100:101]
	v_pk_mul_f32 v[32:33], v[44:45], s[100:101]
	v_pk_mul_f32 v[54:55], v[38:39], s[100:101]
	v_pk_mul_f32 v[56:57], v[40:41], s[100:101]
	v_exp_f32_e32 v30, v30
	v_exp_f32_e32 v31, v31
	v_exp_f32_e32 v32, v32
	v_exp_f32_e32 v33, v33
	v_exp_f32_e32 v54, v54
	v_exp_f32_e32 v55, v55
	v_exp_f32_e32 v56, v56
	v_exp_f32_e32 v57, v57
	v_pk_add_f32 v[30:31], v[30:31], s[98:99]
	v_pk_add_f32 v[32:33], v[32:33], s[98:99]
	v_pk_add_f32 v[54:55], v[54:55], s[98:99]
	v_pk_add_f32 v[56:57], v[56:57], s[98:99]
	v_rcp_f32_e32 v30, v30
	v_rcp_f32_e32 v31, v31
	v_rcp_f32_e32 v32, v32
	v_rcp_f32_e32 v33, v33
	v_rcp_f32_e32 v54, v54
	v_rcp_f32_e32 v55, v55
	v_rcp_f32_e32 v56, v56
	v_rcp_f32_e32 v57, v57
	v_pk_mul_f32 v[42:43], v[42:43], v[74:75]
	v_pk_mul_f32 v[44:45], v[44:45], v[76:77]
	v_pk_mul_f32 v[38:39], v[38:39], v[70:71]
	v_pk_mul_f32 v[40:41], v[40:41], v[72:73]
	v_pk_mul_f32 v[42:43], v[42:43], v[30:31]
	v_pk_mul_f32 v[44:45], v[44:45], v[32:33]
	v_pk_mul_f32 v[38:39], v[38:39], v[54:55]
	v_pk_mul_f32 v[40:41], v[40:41], v[56:57]
	v_pk_mul_f32 v[30:31], v[34:35], s[100:101]
	v_pk_mul_f32 v[32:33], v[36:37], s[100:101]
	v_pk_mul_f32 v[54:55], v[82:83], s[100:101]
	v_pk_mul_f32 v[56:57], v[84:85], s[100:101]
	v_exp_f32_e32 v30, v30
	v_exp_f32_e32 v31, v31
	v_exp_f32_e32 v32, v32
	v_exp_f32_e32 v33, v33
	v_exp_f32_e32 v54, v54
	v_exp_f32_e32 v55, v55
	v_exp_f32_e32 v56, v56
	v_exp_f32_e32 v57, v57
	v_pk_add_f32 v[30:31], v[30:31], s[98:99]
	v_pk_add_f32 v[32:33], v[32:33], s[98:99]
	v_pk_add_f32 v[54:55], v[54:55], s[98:99]
	v_pk_add_f32 v[56:57], v[56:57], s[98:99]
	v_rcp_f32_e32 v30, v30
	v_rcp_f32_e32 v31, v31
	v_rcp_f32_e32 v32, v32
	v_rcp_f32_e32 v33, v33
	v_rcp_f32_e32 v54, v54
	v_rcp_f32_e32 v55, v55
	v_rcp_f32_e32 v56, v56
	v_rcp_f32_e32 v57, v57
	v_pk_mul_f32 v[34:35], v[34:35], v[66:67]
	v_pk_mul_f32 v[36:37], v[36:37], v[68:69]
	v_pk_mul_f32 v[82:83], v[82:83], v[98:99]
	v_pk_mul_f32 v[84:85], v[84:85], v[100:101]
	v_pk_mul_f32 v[34:35], v[34:35], v[30:31]
	v_pk_mul_f32 v[36:37], v[36:37], v[32:33]
	v_pk_mul_f32 v[82:83], v[82:83], v[54:55]
	v_pk_mul_f32 v[84:85], v[84:85], v[56:57]
	s_add_u32 s48, s88, 0x9000000
	s_addc_u32 s49, s89, 0
	v_cvt_pk_bf16_f32 v134, v62, v63
	v_cvt_pk_bf16_f32 v135, v64, v65
	v_cvt_pk_bf16_f32 v136, v42, v43
	v_cvt_pk_bf16_f32 v137, v44, v45
	global_store_dwordx4 v244, v[134:137], s[48:49]
	v_add_u32_e32 v244, 0x1600, v244
	v_cvt_pk_bf16_f32 v74, v50, v51
	v_cvt_pk_bf16_f32 v75, v52, v53
	v_cvt_pk_bf16_f32 v76, v38, v39
	v_cvt_pk_bf16_f32 v77, v40, v41
	global_store_dwordx4 v244, v[74:77], s[48:49]
	v_add_u32_e32 v244, 0x1600, v244
	v_cvt_pk_bf16_f32 v134, v46, v47
	v_cvt_pk_bf16_f32 v135, v48, v49
	v_cvt_pk_bf16_f32 v136, v34, v35
	v_cvt_pk_bf16_f32 v137, v36, v37
	global_store_dwordx4 v244, v[134:137], s[48:49]
	v_add_u32_e32 v244, 0x1600, v244
	v_cvt_pk_bf16_f32 v74, v142, v143
	v_cvt_pk_bf16_f32 v75, v144, v145
	v_cvt_pk_bf16_f32 v76, v82, v83
	v_cvt_pk_bf16_f32 v77, v84, v85
	global_store_dwordx4 v244, v[74:77], s[48:49]
	v_add_u32_e32 v244, 0xffffbe00, v244
	s_waitcnt lgkmcnt(0)
	v_mov_b32_dpp v162, v2 row_shr:1 row_mask:0xf bank_mask:0xf
	v_mov_b32_dpp v166, v26 row_shr:1 row_mask:0xf bank_mask:0xf
	v_mov_b32_dpp v163, v3 row_shr:1 row_mask:0xf bank_mask:0xf
	v_mov_b32_dpp v167, v27 row_shr:1 row_mask:0xf bank_mask:0xf
	v_mov_b32_dpp v164, v4 row_shr:1 row_mask:0xf bank_mask:0xf
	v_mov_b32_dpp v168, v28 row_shr:1 row_mask:0xf bank_mask:0xf
	v_mov_b32_dpp v165, v5 row_shr:1 row_mask:0xf bank_mask:0xf
	v_mov_b32_dpp v169, v29 row_shr:1 row_mask:0xf bank_mask:0xf
	v_pk_fma_f32 v[26:27], v[154:155], v[26:27], v[158:159]
	v_pk_fma_f32 v[28:29], v[156:157], v[28:29], v[160:161]
	v_pk_fma_f32 v[26:27], v[150:151], v[2:3], v[26:27]
	v_pk_fma_f32 v[28:29], v[152:153], v[4:5], v[28:29]
	v_pk_fma_f32 v[26:27], v[146:147], v[6:7], v[26:27]
	v_pk_fma_f32 v[28:29], v[148:149], v[8:9], v[28:29]
	v_pk_fma_f32 v[2:3], v[154:155], v[2:3], v[158:159]
	v_pk_fma_f32 v[4:5], v[156:157], v[4:5], v[160:161]
	v_pk_fma_f32 v[2:3], v[150:151], v[6:7], v[2:3]
	v_pk_fma_f32 v[4:5], v[152:153], v[8:9], v[4:5]
	v_pk_fma_f32 v[2:3], v[146:147], v[10:11], v[2:3]
	v_pk_fma_f32 v[4:5], v[148:149], v[12:13], v[4:5]
	v_pk_fma_f32 v[6:7], v[154:155], v[6:7], v[158:159]
	v_pk_fma_f32 v[8:9], v[156:157], v[8:9], v[160:161]
	v_pk_fma_f32 v[6:7], v[150:151], v[10:11], v[6:7]
	v_pk_fma_f32 v[8:9], v[152:153], v[12:13], v[8:9]
	v_pk_fma_f32 v[6:7], v[146:147], v[166:167], v[6:7]
	v_pk_fma_f32 v[8:9], v[148:149], v[168:169], v[8:9]
	v_pk_fma_f32 v[10:11], v[154:155], v[10:11], v[158:159]
	v_pk_fma_f32 v[12:13], v[156:157], v[12:13], v[160:161]
	v_pk_fma_f32 v[10:11], v[150:151], v[166:167], v[10:11]
	v_pk_fma_f32 v[12:13], v[152:153], v[168:169], v[12:13]
	v_pk_fma_f32 v[10:11], v[146:147], v[162:163], v[10:11]
	v_pk_fma_f32 v[12:13], v[148:149], v[164:165], v[12:13]
	v_pk_mul_f32 v[30:31], v[10:11], s[100:101]
	v_pk_mul_f32 v[32:33], v[12:13], s[100:101]
	v_pk_mul_f32 v[54:55], v[6:7], s[100:101]
	v_pk_mul_f32 v[56:57], v[8:9], s[100:101]
	v_exp_f32_e32 v30, v30
	v_exp_f32_e32 v31, v31
	v_exp_f32_e32 v32, v32
	v_exp_f32_e32 v33, v33
	v_exp_f32_e32 v54, v54
	v_exp_f32_e32 v55, v55
	v_exp_f32_e32 v56, v56
	v_exp_f32_e32 v57, v57
	v_pk_add_f32 v[30:31], v[30:31], s[98:99]
	v_pk_add_f32 v[32:33], v[32:33], s[98:99]
	v_pk_add_f32 v[54:55], v[54:55], s[98:99]
	v_pk_add_f32 v[56:57], v[56:57], s[98:99]
	v_rcp_f32_e32 v30, v30
	v_rcp_f32_e32 v31, v31
	v_rcp_f32_e32 v32, v32
	v_rcp_f32_e32 v33, v33
	v_rcp_f32_e32 v54, v54
	v_rcp_f32_e32 v55, v55
	v_rcp_f32_e32 v56, v56
	v_rcp_f32_e32 v57, v57
	v_pk_mul_f32 v[10:11], v[10:11], v[22:23]
	v_pk_mul_f32 v[12:13], v[12:13], v[24:25]
	v_pk_mul_f32 v[6:7], v[6:7], v[18:19]
	v_pk_mul_f32 v[8:9], v[8:9], v[20:21]
	v_pk_mul_f32 v[10:11], v[10:11], v[30:31]
	v_pk_mul_f32 v[12:13], v[12:13], v[32:33]
	v_pk_mul_f32 v[6:7], v[6:7], v[54:55]
	v_pk_mul_f32 v[8:9], v[8:9], v[56:57]
	v_pk_mul_f32 v[30:31], v[2:3], s[100:101]
	v_pk_mul_f32 v[32:33], v[4:5], s[100:101]
	v_pk_mul_f32 v[54:55], v[26:27], s[100:101]
	v_pk_mul_f32 v[56:57], v[28:29], s[100:101]
	v_exp_f32_e32 v30, v30
	v_exp_f32_e32 v31, v31
	v_exp_f32_e32 v32, v32
	v_exp_f32_e32 v33, v33
	v_exp_f32_e32 v54, v54
	v_exp_f32_e32 v55, v55
	v_exp_f32_e32 v56, v56
	v_exp_f32_e32 v57, v57
	v_pk_add_f32 v[30:31], v[30:31], s[98:99]
	v_pk_add_f32 v[32:33], v[32:33], s[98:99]
	v_pk_add_f32 v[54:55], v[54:55], s[98:99]
	v_pk_add_f32 v[56:57], v[56:57], s[98:99]
	v_rcp_f32_e32 v30, v30
	v_rcp_f32_e32 v31, v31
	v_rcp_f32_e32 v32, v32
	v_rcp_f32_e32 v33, v33
	v_rcp_f32_e32 v54, v54
	v_rcp_f32_e32 v55, v55
	v_rcp_f32_e32 v56, v56
	v_rcp_f32_e32 v57, v57
	v_pk_mul_f32 v[2:3], v[2:3], v[14:15]
	v_pk_mul_f32 v[4:5], v[4:5], v[16:17]
	v_pk_mul_f32 v[26:27], v[26:27], v[58:59]
	v_pk_mul_f32 v[28:29], v[28:29], v[60:61]
	v_pk_mul_f32 v[2:3], v[2:3], v[30:31]
	v_pk_mul_f32 v[4:5], v[4:5], v[32:33]
	v_pk_mul_f32 v[26:27], v[26:27], v[54:55]
	v_pk_mul_f32 v[28:29], v[28:29], v[56:57]
	v_add_u32_e32 v244, 0xb0000, v244
	v_cvt_pk_bf16_f32 v110, v94, v95
	v_cvt_pk_bf16_f32 v111, v96, v97
	v_cvt_pk_bf16_f32 v112, v10, v11
	v_cvt_pk_bf16_f32 v113, v12, v13
	global_store_dwordx4 v244, v[110:113], s[48:49]
	v_add_u32_e32 v244, 0x1600, v244
	v_cvt_pk_bf16_f32 v22, v90, v91
	v_cvt_pk_bf16_f32 v23, v92, v93
	v_cvt_pk_bf16_f32 v24, v6, v7
	v_cvt_pk_bf16_f32 v25, v8, v9
	global_store_dwordx4 v244, v[22:25], s[48:49]
	v_add_u32_e32 v244, 0x1600, v244
	v_cvt_pk_bf16_f32 v110, v86, v87
	v_cvt_pk_bf16_f32 v111, v88, v89
	v_cvt_pk_bf16_f32 v112, v2, v3
	v_cvt_pk_bf16_f32 v113, v4, v5
	global_store_dwordx4 v244, v[110:113], s[48:49]
	v_add_u32_e32 v244, 0x1600, v244
	v_cvt_pk_bf16_f32 v22, v114, v115
	v_cvt_pk_bf16_f32 v23, v116, v117
	v_cvt_pk_bf16_f32 v24, v26, v27
	v_cvt_pk_bf16_f32 v25, v28, v29
	global_store_dwordx4 v244, v[22:25], s[48:49]
	s_cmp_lg_u32 s50, 1
	s_cselect_b64 s[8:9], -1, 0
	s_andn2_b64 vcc, exec, s[4:5]
	s_mov_b64 s[4:5], -1
	s_cbranch_vccnz .LBB0_553
	s_andn2_b64 vcc, exec, s[16:17]
	s_mov_b32 s3, s40
	s_mov_b64 s[28:29], s[94:95]
	s_mov_b64 s[4:5], s[36:37]
	s_cbranch_vccnz .LBB0_590
	s_ashr_i32 s3, s40, 5
	s_mul_hi_i32 s4, s3, 0x5800
	s_mulk_i32 s3, 0x5800
	v_readlane_b32 s5, v255, 14
	s_add_u32 s28, s5, s3
	v_readlane_b32 s3, v255, 15
	s_addc_u32 s29, s3, s4
	s_mov_b32 s3, s38
	s_mov_b64 s[4:5], s[62:63]

.Lnepib_j0:
	s_waitcnt lgkmcnt(0)
	ds_read_b128 v[162:165], v227 offset:4608
	ds_read_b128 v[166:169], v227 offset:5632
	v_mov_b32_dpp v118, v78 row_shr:1 row_mask:0xf bank_mask:0xf
	v_mov_b32_dpp v122, v138 row_shr:1 row_mask:0xf bank_mask:0xf
	v_mov_b32_dpp v119, v79 row_shr:1 row_mask:0xf bank_mask:0xf
	v_mov_b32_dpp v123, v139 row_shr:1 row_mask:0xf bank_mask:0xf
	v_mov_b32_dpp v120, v80 row_shr:1 row_mask:0xf bank_mask:0xf
	v_mov_b32_dpp v124, v140 row_shr:1 row_mask:0xf bank_mask:0xf
	v_mov_b32_dpp v121, v81 row_shr:1 row_mask:0xf bank_mask:0xf
	v_mov_b32_dpp v125, v141 row_shr:1 row_mask:0xf bank_mask:0xf
	v_pk_fma_f32 v[138:139], v[204:205], v[138:139], v[208:209]
	v_pk_fma_f32 v[140:141], v[206:207], v[140:141], v[210:211]
	v_pk_fma_f32 v[138:139], v[200:201], v[78:79], v[138:139]
	v_pk_fma_f32 v[140:141], v[202:203], v[80:81], v[140:141]
	v_pk_fma_f32 v[138:139], v[196:197], v[130:131], v[138:139]
	v_pk_fma_f32 v[140:141], v[198:199], v[132:133], v[140:141]
	v_pk_fma_f32 v[78:79], v[204:205], v[78:79], v[208:209]
	v_pk_fma_f32 v[80:81], v[206:207], v[80:81], v[210:211]
	v_pk_fma_f32 v[78:79], v[200:201], v[130:131], v[78:79]
	v_pk_fma_f32 v[80:81], v[202:203], v[132:133], v[80:81]
	v_pk_fma_f32 v[78:79], v[196:197], v[134:135], v[78:79]
	v_pk_fma_f32 v[80:81], v[198:199], v[136:137], v[80:81]
	v_pk_fma_f32 v[130:131], v[204:205], v[130:131], v[208:209]
	v_pk_fma_f32 v[132:133], v[206:207], v[132:133], v[210:211]
	v_pk_fma_f32 v[130:131], v[200:201], v[134:135], v[130:131]
	v_pk_fma_f32 v[132:133], v[202:203], v[136:137], v[132:133]
	v_pk_fma_f32 v[130:131], v[196:197], v[122:123], v[130:131]
	v_pk_fma_f32 v[132:133], v[198:199], v[124:125], v[132:133]
	v_pk_fma_f32 v[134:135], v[204:205], v[134:135], v[208:209]
	v_pk_fma_f32 v[136:137], v[206:207], v[136:137], v[210:211]
	v_pk_fma_f32 v[134:135], v[200:201], v[122:123], v[134:135]
	v_pk_fma_f32 v[136:137], v[202:203], v[124:125], v[136:137]
	v_pk_fma_f32 v[134:135], v[196:197], v[118:119], v[134:135]
	v_pk_fma_f32 v[136:137], v[198:199], v[120:121], v[136:137]
	s_cmp_lg_u32 s54, 0
	s_cbranch_scc1 .Lnepib_np0
	v_cmp_eq_u32_e32 vcc, 0, v224
	s_and_saveexec_b64 s[8:9], vcc
	s_add_u32 s52, s88, 0x2d00000
	s_addc_u32 s53, s89, 0
	global_store_dwordx4 v229, v[134:137], s[52:53] offset:0
	global_store_dwordx4 v231, v[130:133], s[52:53] offset:0
	s_or_b64 exec, exec, s[8:9]
	s_nop 1
.Lnepib_np0:
	s_waitcnt lgkmcnt(0)
	ds_read_b128 v[146:149], v226 offset:0
	ds_read_b128 v[150:153], v226 offset:1024
	ds_read_b128 v[154:157], v226 offset:2048
	ds_read_b128 v[158:161], v226 offset:3072
	s_cmp_eq_u32 s54, 0
	s_cbranch_scc1 .Lnepib_z2
	ds_read_b128 v[118:121], v227 offset:0
	ds_read_b128 v[122:125], v227 offset:1024
	s_branch .Lnepib_j2

.Lnepib_j2:
	v_mov_b32_dpp v162, v102 row_shr:1 row_mask:0xf bank_mask:0xf
	v_mov_b32_dpp v166, v126 row_shr:1 row_mask:0xf bank_mask:0xf
	v_mov_b32_dpp v163, v103 row_shr:1 row_mask:0xf bank_mask:0xf
	v_mov_b32_dpp v167, v127 row_shr:1 row_mask:0xf bank_mask:0xf
	v_mov_b32_dpp v164, v104 row_shr:1 row_mask:0xf bank_mask:0xf
	v_mov_b32_dpp v168, v128 row_shr:1 row_mask:0xf bank_mask:0xf
	v_mov_b32_dpp v165, v105 row_shr:1 row_mask:0xf bank_mask:0xf
	v_mov_b32_dpp v169, v129 row_shr:1 row_mask:0xf bank_mask:0xf
	v_pk_fma_f32 v[126:127], v[204:205], v[126:127], v[208:209]
	v_pk_fma_f32 v[128:129], v[206:207], v[128:129], v[210:211]
	v_pk_fma_f32 v[126:127], v[200:201], v[102:103], v[126:127]
	v_pk_fma_f32 v[128:129], v[202:203], v[104:105], v[128:129]
	v_pk_fma_f32 v[126:127], v[196:197], v[106:107], v[126:127]
	v_pk_fma_f32 v[128:129], v[198:199], v[108:109], v[128:129]
	v_pk_fma_f32 v[102:103], v[204:205], v[102:103], v[208:209]
	v_pk_fma_f32 v[104:105], v[206:207], v[104:105], v[210:211]
	v_pk_fma_f32 v[102:103], v[200:201], v[106:107], v[102:103]
	v_pk_fma_f32 v[104:105], v[202:203], v[108:109], v[104:105]
	v_pk_fma_f32 v[102:103], v[196:197], v[110:111], v[102:103]
	v_pk_fma_f32 v[104:105], v[198:199], v[112:113], v[104:105]
	v_pk_fma_f32 v[106:107], v[204:205], v[106:107], v[208:209]
	v_pk_fma_f32 v[108:109], v[206:207], v[108:109], v[210:211]
	v_pk_fma_f32 v[106:107], v[200:201], v[110:111], v[106:107]
	v_pk_fma_f32 v[108:109], v[202:203], v[112:113], v[108:109]
	v_pk_fma_f32 v[106:107], v[196:197], v[166:167], v[106:107]
	v_pk_fma_f32 v[108:109], v[198:199], v[168:169], v[108:109]
	v_pk_fma_f32 v[110:111], v[204:205], v[110:111], v[208:209]
	v_pk_fma_f32 v[112:113], v[206:207], v[112:113], v[210:211]
	v_pk_fma_f32 v[110:111], v[200:201], v[166:167], v[110:111]
	v_pk_fma_f32 v[112:113], v[202:203], v[168:169], v[112:113]
	v_pk_fma_f32 v[110:111], v[196:197], v[162:163], v[110:111]
	v_pk_fma_f32 v[112:113], v[198:199], v[164:165], v[112:113]
	s_waitcnt lgkmcnt(0)
	ds_read_b128 v[162:165], v227 offset:4096
	ds_read_b128 v[166:169], v227 offset:5120
	v_mov_b32_dpp v118, v46 row_shr:1 row_mask:0xf bank_mask:0xf
	v_mov_b32_dpp v122, v142 row_shr:1 row_mask:0xf bank_mask:0xf
	v_mov_b32_dpp v119, v47 row_shr:1 row_mask:0xf bank_mask:0xf
	v_mov_b32_dpp v123, v143 row_shr:1 row_mask:0xf bank_mask:0xf
	v_mov_b32_dpp v120, v48 row_shr:1 row_mask:0xf bank_mask:0xf
	v_mov_b32_dpp v124, v144 row_shr:1 row_mask:0xf bank_mask:0xf
	v_mov_b32_dpp v121, v49 row_shr:1 row_mask:0xf bank_mask:0xf
	v_mov_b32_dpp v125, v145 row_shr:1 row_mask:0xf bank_mask:0xf
	v_pk_fma_f32 v[142:143], v[154:155], v[142:143], v[158:159]
	v_pk_fma_f32 v[144:145], v[156:157], v[144:145], v[160:161]
	v_pk_fma_f32 v[142:143], v[150:151], v[46:47], v[142:143]
	v_pk_fma_f32 v[144:145], v[152:153], v[48:49], v[144:145]
	v_pk_fma_f32 v[142:143], v[146:147], v[50:51], v[142:143]
	v_pk_fma_f32 v[144:145], v[148:149], v[52:53], v[144:145]
	v_pk_fma_f32 v[46:47], v[154:155], v[46:47], v[158:159]
	v_pk_fma_f32 v[48:49], v[156:157], v[48:49], v[160:161]
	v_pk_fma_f32 v[46:47], v[150:151], v[50:51], v[46:47]
	v_pk_fma_f32 v[48:49], v[152:153], v[52:53], v[48:49]
	v_pk_fma_f32 v[46:47], v[146:147], v[62:63], v[46:47]
	v_pk_fma_f32 v[48:49], v[148:149], v[64:65], v[48:49]
	v_pk_fma_f32 v[50:51], v[154:155], v[50:51], v[158:159]
	v_pk_fma_f32 v[52:53], v[156:157], v[52:53], v[160:161]
	v_pk_fma_f32 v[50:51], v[150:151], v[62:63], v[50:51]
	v_pk_fma_f32 v[52:53], v[152:153], v[64:65], v[52:53]
	v_pk_fma_f32 v[50:51], v[146:147], v[122:123], v[50:51]
	v_pk_fma_f32 v[52:53], v[148:149], v[124:125], v[52:53]
	v_pk_fma_f32 v[62:63], v[154:155], v[62:63], v[158:159]
	v_pk_fma_f32 v[64:65], v[156:157], v[64:65], v[160:161]
	v_pk_fma_f32 v[62:63], v[150:151], v[122:123], v[62:63]
	v_pk_fma_f32 v[64:65], v[152:153], v[124:125], v[64:65]
	v_pk_fma_f32 v[62:63], v[146:147], v[118:119], v[62:63]
	v_pk_fma_f32 v[64:65], v[148:149], v[120:121], v[64:65]
	s_cmp_lg_u32 s54, 0
	s_cbranch_scc1 .Lnepib_np2
	v_cmp_eq_u32_e32 vcc, 0, v224
	s_and_saveexec_b64 s[8:9], vcc
	s_add_u32 s52, s88, 0x2d00000
	s_addc_u32 s53, s89, 0
	global_store_dwordx4 v228, v[62:65], s[52:53] offset:0
	global_store_dwordx4 v230, v[50:53], s[52:53] offset:0
	s_or_b64 exec, exec, s[8:9]
	s_nop 1
.Lnepib_np2:
	v_pk_mul_f32 v[30:31], v[62:63], s[100:101]
	v_pk_mul_f32 v[32:33], v[64:65], s[100:101]
	v_pk_mul_f32 v[54:55], v[50:51], s[100:101]
	v_pk_mul_f32 v[56:57], v[52:53], s[100:101]
	v_exp_f32_e32 v30, v30
	v_exp_f32_e32 v31, v31
	v_exp_f32_e32 v32, v32
	v_exp_f32_e32 v33, v33
	v_exp_f32_e32 v54, v54
	v_exp_f32_e32 v55, v55
	v_exp_f32_e32 v56, v56
	v_exp_f32_e32 v57, v57
	v_pk_add_f32 v[30:31], v[30:31], s[98:99]
	v_pk_add_f32 v[32:33], v[32:33], s[98:99]
	v_pk_add_f32 v[54:55], v[54:55], s[98:99]
	v_pk_add_f32 v[56:57], v[56:57], s[98:99]
	v_rcp_f32_e32 v30, v30
	v_rcp_f32_e32 v31, v31
	v_rcp_f32_e32 v32, v32
	v_rcp_f32_e32 v33, v33
	v_rcp_f32_e32 v54, v54
	v_rcp_f32_e32 v55, v55
	v_rcp_f32_e32 v56, v56
	v_rcp_f32_e32 v57, v57
	v_pk_mul_f32 v[62:63], v[62:63], v[134:135]
	v_pk_mul_f32 v[64:65], v[64:65], v[136:137]
	v_pk_mul_f32 v[50:51], v[50:51], v[130:131]
	v_pk_mul_f32 v[52:53], v[52:53], v[132:133]
	v_pk_mul_f32 v[62:63], v[62:63], v[30:31]
	v_pk_mul_f32 v[64:65], v[64:65], v[32:33]
	v_pk_mul_f32 v[50:51], v[50:51], v[54:55]
	v_pk_mul_f32 v[52:53], v[52:53], v[56:57]
	v_pk_mul_f32 v[30:31], v[46:47], s[100:101]
	v_pk_mul_f32 v[32:33], v[48:49], s[100:101]
	v_pk_mul_f32 v[54:55], v[142:143], s[100:101]
	v_pk_mul_f32 v[56:57], v[144:145], s[100:101]
	v_exp_f32_e32 v30, v30
	v_exp_f32_e32 v31, v31
	v_exp_f32_e32 v32, v32
	v_exp_f32_e32 v33, v33
	v_exp_f32_e32 v54, v54
	v_exp_f32_e32 v55, v55
	v_exp_f32_e32 v56, v56
	v_exp_f32_e32 v57, v57
	v_pk_add_f32 v[30:31], v[30:31], s[98:99]
	v_pk_add_f32 v[32:33], v[32:33], s[98:99]
	v_pk_add_f32 v[54:55], v[54:55], s[98:99]
	v_pk_add_f32 v[56:57], v[56:57], s[98:99]
	v_rcp_f32_e32 v30, v30
	v_rcp_f32_e32 v31, v31
	v_rcp_f32_e32 v32, v32
	v_rcp_f32_e32 v33, v33
	v_rcp_f32_e32 v54, v54
	v_rcp_f32_e32 v55, v55
	v_rcp_f32_e32 v56, v56
	v_rcp_f32_e32 v57, v57
	v_pk_mul_f32 v[46:47], v[46:47], v[78:79]
	v_pk_mul_f32 v[48:49], v[48:49], v[80:81]
	v_pk_mul_f32 v[142:143], v[142:143], v[138:139]
	v_pk_mul_f32 v[144:145], v[144:145], v[140:141]
	v_pk_mul_f32 v[46:47], v[46:47], v[30:31]
	v_pk_mul_f32 v[48:49], v[48:49], v[32:33]
	v_pk_mul_f32 v[142:143], v[142:143], v[54:55]
	v_pk_mul_f32 v[144:145], v[144:145], v[56:57]
	s_waitcnt lgkmcnt(0)
	ds_read_b128 v[196:199], v226 offset:528
	ds_read_b128 v[200:203], v226 offset:1552
	ds_read_b128 v[204:207], v226 offset:2576
	ds_read_b128 v[208:211], v226 offset:3600
	s_cmp_eq_u32 s54, 0
	s_cbranch_scc1 .Lnepib_z4
	ds_read_b128 v[118:121], v227 offset:528
	ds_read_b128 v[122:125], v227 offset:1552
	s_branch .Lnepib_j4

.Lnepib_j4:
	v_mov_b32_dpp v162, v86 row_shr:1 row_mask:0xf bank_mask:0xf
	v_mov_b32_dpp v166, v114 row_shr:1 row_mask:0xf bank_mask:0xf
	v_mov_b32_dpp v163, v87 row_shr:1 row_mask:0xf bank_mask:0xf
	v_mov_b32_dpp v167, v115 row_shr:1 row_mask:0xf bank_mask:0xf
	v_mov_b32_dpp v164, v88 row_shr:1 row_mask:0xf bank_mask:0xf
	v_mov_b32_dpp v168, v116 row_shr:1 row_mask:0xf bank_mask:0xf
	v_mov_b32_dpp v165, v89 row_shr:1 row_mask:0xf bank_mask:0xf
	v_mov_b32_dpp v169, v117 row_shr:1 row_mask:0xf bank_mask:0xf
	v_pk_fma_f32 v[114:115], v[154:155], v[114:115], v[158:159]
	v_pk_fma_f32 v[116:117], v[156:157], v[116:117], v[160:161]
	v_pk_fma_f32 v[114:115], v[150:151], v[86:87], v[114:115]
	v_pk_fma_f32 v[116:117], v[152:153], v[88:89], v[116:117]
	v_pk_fma_f32 v[114:115], v[146:147], v[90:91], v[114:115]
	v_pk_fma_f32 v[116:117], v[148:149], v[92:93], v[116:117]
	v_pk_fma_f32 v[86:87], v[154:155], v[86:87], v[158:159]
	v_pk_fma_f32 v[88:89], v[156:157], v[88:89], v[160:161]
	v_pk_fma_f32 v[86:87], v[150:151], v[90:91], v[86:87]
	v_pk_fma_f32 v[88:89], v[152:153], v[92:93], v[88:89]
	v_pk_fma_f32 v[86:87], v[146:147], v[94:95], v[86:87]
	v_pk_fma_f32 v[88:89], v[148:149], v[96:97], v[88:89]
	v_pk_fma_f32 v[90:91], v[154:155], v[90:91], v[158:159]
	v_pk_fma_f32 v[92:93], v[156:157], v[92:93], v[160:161]
	v_pk_fma_f32 v[90:91], v[150:151], v[94:95], v[90:91]
	v_pk_fma_f32 v[92:93], v[152:153], v[96:97], v[92:93]
	v_pk_fma_f32 v[90:91], v[146:147], v[166:167], v[90:91]
	v_pk_fma_f32 v[92:93], v[148:149], v[168:169], v[92:93]
	v_pk_fma_f32 v[94:95], v[154:155], v[94:95], v[158:159]
	v_pk_fma_f32 v[96:97], v[156:157], v[96:97], v[160:161]
	v_pk_fma_f32 v[94:95], v[150:151], v[166:167], v[94:95]
	v_pk_fma_f32 v[96:97], v[152:153], v[168:169], v[96:97]
	v_pk_fma_f32 v[94:95], v[146:147], v[162:163], v[94:95]
	v_pk_fma_f32 v[96:97], v[148:149], v[164:165], v[96:97]
	v_pk_mul_f32 v[30:31], v[94:95], s[100:101]
	v_pk_mul_f32 v[32:33], v[96:97], s[100:101]
	v_pk_mul_f32 v[54:55], v[90:91], s[100:101]
	v_pk_mul_f32 v[56:57], v[92:93], s[100:101]
	v_exp_f32_e32 v30, v30
	v_exp_f32_e32 v31, v31
	v_exp_f32_e32 v32, v32
	v_exp_f32_e32 v33, v33
	v_exp_f32_e32 v54, v54
	v_exp_f32_e32 v55, v55
	v_exp_f32_e32 v56, v56
	v_exp_f32_e32 v57, v57
	v_pk_add_f32 v[30:31], v[30:31], s[98:99]
	v_pk_add_f32 v[32:33], v[32:33], s[98:99]
	v_pk_add_f32 v[54:55], v[54:55], s[98:99]
	v_pk_add_f32 v[56:57], v[56:57], s[98:99]
	v_rcp_f32_e32 v30, v30
	v_rcp_f32_e32 v31, v31
	v_rcp_f32_e32 v32, v32
	v_rcp_f32_e32 v33, v33
	v_rcp_f32_e32 v54, v54
	v_rcp_f32_e32 v55, v55
	v_rcp_f32_e32 v56, v56
	v_rcp_f32_e32 v57, v57
	v_pk_mul_f32 v[94:95], v[94:95], v[110:111]
	v_pk_mul_f32 v[96:97], v[96:97], v[112:113]
	v_pk_mul_f32 v[90:91], v[90:91], v[106:107]
	v_pk_mul_f32 v[92:93], v[92:93], v[108:109]
	v_pk_mul_f32 v[94:95], v[94:95], v[30:31]
	v_pk_mul_f32 v[96:97], v[96:97], v[32:33]
	v_pk_mul_f32 v[90:91], v[90:91], v[54:55]
	v_pk_mul_f32 v[92:93], v[92:93], v[56:57]
	v_pk_mul_f32 v[30:31], v[86:87], s[100:101]
	v_pk_mul_f32 v[32:33], v[88:89], s[100:101]
	v_pk_mul_f32 v[54:55], v[114:115], s[100:101]
	v_pk_mul_f32 v[56:57], v[116:117], s[100:101]
	v_exp_f32_e32 v30, v30
	v_exp_f32_e32 v31, v31
	v_exp_f32_e32 v32, v32
	v_exp_f32_e32 v33, v33
	v_exp_f32_e32 v54, v54
	v_exp_f32_e32 v55, v55
	v_exp_f32_e32 v56, v56
	v_exp_f32_e32 v57, v57
	v_pk_add_f32 v[30:31], v[30:31], s[98:99]
	v_pk_add_f32 v[32:33], v[32:33], s[98:99]
	v_pk_add_f32 v[54:55], v[54:55], s[98:99]
	v_pk_add_f32 v[56:57], v[56:57], s[98:99]
	v_rcp_f32_e32 v30, v30
	v_rcp_f32_e32 v31, v31
	v_rcp_f32_e32 v32, v32
	v_rcp_f32_e32 v33, v33
	v_rcp_f32_e32 v54, v54
	v_rcp_f32_e32 v55, v55
	v_rcp_f32_e32 v56, v56
	v_rcp_f32_e32 v57, v57
	v_pk_mul_f32 v[86:87], v[86:87], v[102:103]
	v_pk_mul_f32 v[88:89], v[88:89], v[104:105]
	v_pk_mul_f32 v[114:115], v[114:115], v[126:127]
	v_pk_mul_f32 v[116:117], v[116:117], v[128:129]
	v_pk_mul_f32 v[86:87], v[86:87], v[30:31]
	v_pk_mul_f32 v[88:89], v[88:89], v[32:33]
	v_pk_mul_f32 v[114:115], v[114:115], v[54:55]
	v_pk_mul_f32 v[116:117], v[116:117], v[56:57]
	s_waitcnt lgkmcnt(0)
	ds_read_b128 v[162:165], v227 offset:4624
	ds_read_b128 v[166:169], v227 offset:5648
	v_mov_b32_dpp v118, v66 row_shr:1 row_mask:0xf bank_mask:0xf
	v_mov_b32_dpp v122, v98 row_shr:1 row_mask:0xf bank_mask:0xf
	v_mov_b32_dpp v119, v67 row_shr:1 row_mask:0xf bank_mask:0xf
	v_mov_b32_dpp v123, v99 row_shr:1 row_mask:0xf bank_mask:0xf
	v_mov_b32_dpp v120, v68 row_shr:1 row_mask:0xf bank_mask:0xf
	v_mov_b32_dpp v124, v100 row_shr:1 row_mask:0xf bank_mask:0xf
	v_mov_b32_dpp v121, v69 row_shr:1 row_mask:0xf bank_mask:0xf
	v_mov_b32_dpp v125, v101 row_shr:1 row_mask:0xf bank_mask:0xf
	v_pk_fma_f32 v[98:99], v[204:205], v[98:99], v[208:209]
	v_pk_fma_f32 v[100:101], v[206:207], v[100:101], v[210:211]
	v_pk_fma_f32 v[98:99], v[200:201], v[66:67], v[98:99]
	v_pk_fma_f32 v[100:101], v[202:203], v[68:69], v[100:101]
	v_pk_fma_f32 v[98:99], v[196:197], v[70:71], v[98:99]
	v_pk_fma_f32 v[100:101], v[198:199], v[72:73], v[100:101]
	v_pk_fma_f32 v[66:67], v[204:205], v[66:67], v[208:209]
	v_pk_fma_f32 v[68:69], v[206:207], v[68:69], v[210:211]
	v_pk_fma_f32 v[66:67], v[200:201], v[70:71], v[66:67]
	v_pk_fma_f32 v[68:69], v[202:203], v[72:73], v[68:69]
	v_pk_fma_f32 v[66:67], v[196:197], v[74:75], v[66:67]
	v_pk_fma_f32 v[68:69], v[198:199], v[76:77], v[68:69]
	v_pk_fma_f32 v[70:71], v[204:205], v[70:71], v[208:209]
	v_pk_fma_f32 v[72:73], v[206:207], v[72:73], v[210:211]
	v_pk_fma_f32 v[70:71], v[200:201], v[74:75], v[70:71]
	v_pk_fma_f32 v[72:73], v[202:203], v[76:77], v[72:73]
	v_pk_fma_f32 v[70:71], v[196:197], v[122:123], v[70:71]
	v_pk_fma_f32 v[72:73], v[198:199], v[124:125], v[72:73]
	v_pk_fma_f32 v[74:75], v[204:205], v[74:75], v[208:209]
	v_pk_fma_f32 v[76:77], v[206:207], v[76:77], v[210:211]
	v_pk_fma_f32 v[74:75], v[200:201], v[122:123], v[74:75]
	v_pk_fma_f32 v[76:77], v[202:203], v[124:125], v[76:77]
	v_pk_fma_f32 v[74:75], v[196:197], v[118:119], v[74:75]
	v_pk_fma_f32 v[76:77], v[198:199], v[120:121], v[76:77]
	s_cmp_lg_u32 s54, 0
	s_cbranch_scc1 .Lnepib_np4
	v_cmp_eq_u32_e32 vcc, 0, v224
	s_and_saveexec_b64 s[8:9], vcc
	s_add_u32 s52, s88, 0x2d00000
	s_addc_u32 s53, s89, 0
	global_store_dwordx4 v229, v[74:77], s[52:53] offset:16
	global_store_dwordx4 v231, v[70:73], s[52:53] offset:16
	s_or_b64 exec, exec, s[8:9]
	s_nop 1
.Lnepib_np4:
	s_waitcnt lgkmcnt(0)
	ds_read_b128 v[146:149], v226 offset:16
	ds_read_b128 v[150:153], v226 offset:1040
	ds_read_b128 v[154:157], v226 offset:2064
	ds_read_b128 v[158:161], v226 offset:3088
	s_cmp_eq_u32 s54, 0
	s_cbranch_scc1 .Lnepib_z6
	ds_read_b128 v[118:121], v227 offset:16
	ds_read_b128 v[122:125], v227 offset:1040
	s_branch .Lnepib_j6

.Lnepib_j6:
	v_mov_b32_dpp v162, v14 row_shr:1 row_mask:0xf bank_mask:0xf
	v_mov_b32_dpp v166, v58 row_shr:1 row_mask:0xf bank_mask:0xf
	v_mov_b32_dpp v163, v15 row_shr:1 row_mask:0xf bank_mask:0xf
	v_mov_b32_dpp v167, v59 row_shr:1 row_mask:0xf bank_mask:0xf
	v_mov_b32_dpp v164, v16 row_shr:1 row_mask:0xf bank_mask:0xf
	v_mov_b32_dpp v168, v60 row_shr:1 row_mask:0xf bank_mask:0xf
	v_mov_b32_dpp v165, v17 row_shr:1 row_mask:0xf bank_mask:0xf
	v_mov_b32_dpp v169, v61 row_shr:1 row_mask:0xf bank_mask:0xf
	v_pk_fma_f32 v[58:59], v[204:205], v[58:59], v[208:209]
	v_pk_fma_f32 v[60:61], v[206:207], v[60:61], v[210:211]
	v_pk_fma_f32 v[58:59], v[200:201], v[14:15], v[58:59]
	v_pk_fma_f32 v[60:61], v[202:203], v[16:17], v[60:61]
	v_pk_fma_f32 v[58:59], v[196:197], v[18:19], v[58:59]
	v_pk_fma_f32 v[60:61], v[198:199], v[20:21], v[60:61]
	v_pk_fma_f32 v[14:15], v[204:205], v[14:15], v[208:209]
	v_pk_fma_f32 v[16:17], v[206:207], v[16:17], v[210:211]
	v_pk_fma_f32 v[14:15], v[200:201], v[18:19], v[14:15]
	v_pk_fma_f32 v[16:17], v[202:203], v[20:21], v[16:17]
	v_pk_fma_f32 v[14:15], v[196:197], v[22:23], v[14:15]
	v_pk_fma_f32 v[16:17], v[198:199], v[24:25], v[16:17]
	v_pk_fma_f32 v[18:19], v[204:205], v[18:19], v[208:209]
	v_pk_fma_f32 v[20:21], v[206:207], v[20:21], v[210:211]
	v_pk_fma_f32 v[18:19], v[200:201], v[22:23], v[18:19]
	v_pk_fma_f32 v[20:21], v[202:203], v[24:25], v[20:21]
	v_pk_fma_f32 v[18:19], v[196:197], v[166:167], v[18:19]
	v_pk_fma_f32 v[20:21], v[198:199], v[168:169], v[20:21]
	v_pk_fma_f32 v[22:23], v[204:205], v[22:23], v[208:209]
	v_pk_fma_f32 v[24:25], v[206:207], v[24:25], v[210:211]
	v_pk_fma_f32 v[22:23], v[200:201], v[166:167], v[22:23]
	v_pk_fma_f32 v[24:25], v[202:203], v[168:169], v[24:25]
	v_pk_fma_f32 v[22:23], v[196:197], v[162:163], v[22:23]
	v_pk_fma_f32 v[24:25], v[198:199], v[164:165], v[24:25]
	s_waitcnt lgkmcnt(0)
	ds_read_b128 v[162:165], v227 offset:4112
	ds_read_b128 v[166:169], v227 offset:5136
	v_mov_b32_dpp v118, v34 row_shr:1 row_mask:0xf bank_mask:0xf
	v_mov_b32_dpp v122, v82 row_shr:1 row_mask:0xf bank_mask:0xf
	v_mov_b32_dpp v119, v35 row_shr:1 row_mask:0xf bank_mask:0xf
	v_mov_b32_dpp v123, v83 row_shr:1 row_mask:0xf bank_mask:0xf
	v_mov_b32_dpp v120, v36 row_shr:1 row_mask:0xf bank_mask:0xf
	v_mov_b32_dpp v124, v84 row_shr:1 row_mask:0xf bank_mask:0xf
	v_mov_b32_dpp v121, v37 row_shr:1 row_mask:0xf bank_mask:0xf
	v_mov_b32_dpp v125, v85 row_shr:1 row_mask:0xf bank_mask:0xf
	v_pk_fma_f32 v[82:83], v[154:155], v[82:83], v[158:159]
	v_pk_fma_f32 v[84:85], v[156:157], v[84:85], v[160:161]
	v_pk_fma_f32 v[82:83], v[150:151], v[34:35], v[82:83]
	v_pk_fma_f32 v[84:85], v[152:153], v[36:37], v[84:85]
	v_pk_fma_f32 v[82:83], v[146:147], v[38:39], v[82:83]
	v_pk_fma_f32 v[84:85], v[148:149], v[40:41], v[84:85]
	v_pk_fma_f32 v[34:35], v[154:155], v[34:35], v[158:159]
	v_pk_fma_f32 v[36:37], v[156:157], v[36:37], v[160:161]
	v_pk_fma_f32 v[34:35], v[150:151], v[38:39], v[34:35]
	v_pk_fma_f32 v[36:37], v[152:153], v[40:41], v[36:37]
	v_pk_fma_f32 v[34:35], v[146:147], v[42:43], v[34:35]
	v_pk_fma_f32 v[36:37], v[148:149], v[44:45], v[36:37]
	v_pk_fma_f32 v[38:39], v[154:155], v[38:39], v[158:159]
	v_pk_fma_f32 v[40:41], v[156:157], v[40:41], v[160:161]
	v_pk_fma_f32 v[38:39], v[150:151], v[42:43], v[38:39]
	v_pk_fma_f32 v[40:41], v[152:153], v[44:45], v[40:41]
	v_pk_fma_f32 v[38:39], v[146:147], v[122:123], v[38:39]
	v_pk_fma_f32 v[40:41], v[148:149], v[124:125], v[40:41]
	v_pk_fma_f32 v[42:43], v[154:155], v[42:43], v[158:159]
	v_pk_fma_f32 v[44:45], v[156:157], v[44:45], v[160:161]
	v_pk_fma_f32 v[42:43], v[150:151], v[122:123], v[42:43]
	v_pk_fma_f32 v[44:45], v[152:153], v[124:125], v[44:45]
	v_pk_fma_f32 v[42:43], v[146:147], v[118:119], v[42:43]
	v_pk_fma_f32 v[44:45], v[148:149], v[120:121], v[44:45]
	s_cmp_lg_u32 s54, 0
	s_cbranch_scc1 .Lnepib_np6
	v_cmp_eq_u32_e32 vcc, 0, v224
	s_and_saveexec_b64 s[8:9], vcc
	s_add_u32 s52, s88, 0x2d00000
	s_addc_u32 s53, s89, 0
	global_store_dwordx4 v228, v[42:45], s[52:53] offset:16
	global_store_dwordx4 v230, v[38:41], s[52:53] offset:16
	s_or_b64 exec, exec, s[8:9]
	s_nop 1
.Lnepib_np6:
	v_pk_mul_f32 v[30:31], v[42:43], s[100:101]
	v_pk_mul_f32 v[32:33], v[44:45], s[100:101]
	v_pk_mul_f32 v[54:55], v[38:39], s[100:101]
	v_pk_mul_f32 v[56:57], v[40:41], s[100:101]
	v_exp_f32_e32 v30, v30
	v_exp_f32_e32 v31, v31
	v_exp_f32_e32 v32, v32
	v_exp_f32_e32 v33, v33
	v_exp_f32_e32 v54, v54
	v_exp_f32_e32 v55, v55
	v_exp_f32_e32 v56, v56
	v_exp_f32_e32 v57, v57
	v_pk_add_f32 v[30:31], v[30:31], s[98:99]
	v_pk_add_f32 v[32:33], v[32:33], s[98:99]
	v_pk_add_f32 v[54:55], v[54:55], s[98:99]
	v_pk_add_f32 v[56:57], v[56:57], s[98:99]
	v_rcp_f32_e32 v30, v30
	v_rcp_f32_e32 v31, v31
	v_rcp_f32_e32 v32, v32
	v_rcp_f32_e32 v33, v33
	v_rcp_f32_e32 v54, v54
	v_rcp_f32_e32 v55, v55
	v_rcp_f32_e32 v56, v56
	v_rcp_f32_e32 v57, v57
	v_pk_mul_f32 v[42:43], v[42:43], v[74:75]
	v_pk_mul_f32 v[44:45], v[44:45], v[76:77]
	v_pk_mul_f32 v[38:39], v[38:39], v[70:71]
	v_pk_mul_f32 v[40:41], v[40:41], v[72:73]
	v_pk_mul_f32 v[42:43], v[42:43], v[30:31]
	v_pk_mul_f32 v[44:45], v[44:45], v[32:33]
	v_pk_mul_f32 v[38:39], v[38:39], v[54:55]
	v_pk_mul_f32 v[40:41], v[40:41], v[56:57]
	v_pk_mul_f32 v[30:31], v[34:35], s[100:101]
	v_pk_mul_f32 v[32:33], v[36:37], s[100:101]
	v_pk_mul_f32 v[54:55], v[82:83], s[100:101]
	v_pk_mul_f32 v[56:57], v[84:85], s[100:101]
	v_exp_f32_e32 v30, v30
	v_exp_f32_e32 v31, v31
	v_exp_f32_e32 v32, v32
	v_exp_f32_e32 v33, v33
	v_exp_f32_e32 v54, v54
	v_exp_f32_e32 v55, v55
	v_exp_f32_e32 v56, v56
	v_exp_f32_e32 v57, v57
	v_pk_add_f32 v[30:31], v[30:31], s[98:99]
	v_pk_add_f32 v[32:33], v[32:33], s[98:99]
	v_pk_add_f32 v[54:55], v[54:55], s[98:99]
	v_pk_add_f32 v[56:57], v[56:57], s[98:99]
	v_rcp_f32_e32 v30, v30
	v_rcp_f32_e32 v31, v31
	v_rcp_f32_e32 v32, v32
	v_rcp_f32_e32 v33, v33
	v_rcp_f32_e32 v54, v54
	v_rcp_f32_e32 v55, v55
	v_rcp_f32_e32 v56, v56
	v_rcp_f32_e32 v57, v57
	v_pk_mul_f32 v[34:35], v[34:35], v[66:67]
	v_pk_mul_f32 v[36:37], v[36:37], v[68:69]
	v_pk_mul_f32 v[82:83], v[82:83], v[98:99]
	v_pk_mul_f32 v[84:85], v[84:85], v[100:101]
	v_pk_mul_f32 v[34:35], v[34:35], v[30:31]
	v_pk_mul_f32 v[36:37], v[36:37], v[32:33]
	v_pk_mul_f32 v[82:83], v[82:83], v[54:55]
	v_pk_mul_f32 v[84:85], v[84:85], v[56:57]
	s_add_u32 s52, s88, 0x9000000
	s_addc_u32 s53, s89, 0
	v_cvt_pk_bf16_f32 v134, v62, v63
	v_cvt_pk_bf16_f32 v135, v64, v65
	v_cvt_pk_bf16_f32 v136, v42, v43
	v_cvt_pk_bf16_f32 v137, v44, v45
	global_store_dwordx4 v244, v[134:137], s[52:53]
	v_add_u32_e32 v244, 0x1600, v244
	v_cvt_pk_bf16_f32 v74, v50, v51
	v_cvt_pk_bf16_f32 v75, v52, v53
	v_cvt_pk_bf16_f32 v76, v38, v39
	v_cvt_pk_bf16_f32 v77, v40, v41
	global_store_dwordx4 v244, v[74:77], s[52:53]
	v_add_u32_e32 v244, 0x1600, v244
	v_cvt_pk_bf16_f32 v134, v46, v47
	v_cvt_pk_bf16_f32 v135, v48, v49
	v_cvt_pk_bf16_f32 v136, v34, v35
	v_cvt_pk_bf16_f32 v137, v36, v37
	global_store_dwordx4 v244, v[134:137], s[52:53]
	v_add_u32_e32 v244, 0x1600, v244
	v_cvt_pk_bf16_f32 v74, v142, v143
	v_cvt_pk_bf16_f32 v75, v144, v145
	v_cvt_pk_bf16_f32 v76, v82, v83
	v_cvt_pk_bf16_f32 v77, v84, v85
	global_store_dwordx4 v244, v[74:77], s[52:53]
	v_add_u32_e32 v244, 0xffffbe00, v244
	s_waitcnt lgkmcnt(0)
	v_mov_b32_dpp v162, v2 row_shr:1 row_mask:0xf bank_mask:0xf
	v_mov_b32_dpp v166, v26 row_shr:1 row_mask:0xf bank_mask:0xf
	v_mov_b32_dpp v163, v3 row_shr:1 row_mask:0xf bank_mask:0xf
	v_mov_b32_dpp v167, v27 row_shr:1 row_mask:0xf bank_mask:0xf
	v_mov_b32_dpp v164, v4 row_shr:1 row_mask:0xf bank_mask:0xf
	v_mov_b32_dpp v168, v28 row_shr:1 row_mask:0xf bank_mask:0xf
	v_mov_b32_dpp v165, v5 row_shr:1 row_mask:0xf bank_mask:0xf
	v_mov_b32_dpp v169, v29 row_shr:1 row_mask:0xf bank_mask:0xf
	v_pk_fma_f32 v[26:27], v[154:155], v[26:27], v[158:159]
	v_pk_fma_f32 v[28:29], v[156:157], v[28:29], v[160:161]
	v_pk_fma_f32 v[26:27], v[150:151], v[2:3], v[26:27]
	v_pk_fma_f32 v[28:29], v[152:153], v[4:5], v[28:29]
	v_pk_fma_f32 v[26:27], v[146:147], v[6:7], v[26:27]
	v_pk_fma_f32 v[28:29], v[148:149], v[8:9], v[28:29]
	v_pk_fma_f32 v[2:3], v[154:155], v[2:3], v[158:159]
	v_pk_fma_f32 v[4:5], v[156:157], v[4:5], v[160:161]
	v_pk_fma_f32 v[2:3], v[150:151], v[6:7], v[2:3]
	v_pk_fma_f32 v[4:5], v[152:153], v[8:9], v[4:5]
	v_pk_fma_f32 v[2:3], v[146:147], v[10:11], v[2:3]
	v_pk_fma_f32 v[4:5], v[148:149], v[12:13], v[4:5]
	v_pk_fma_f32 v[6:7], v[154:155], v[6:7], v[158:159]
	v_pk_fma_f32 v[8:9], v[156:157], v[8:9], v[160:161]
	v_pk_fma_f32 v[6:7], v[150:151], v[10:11], v[6:7]
	v_pk_fma_f32 v[8:9], v[152:153], v[12:13], v[8:9]
	v_pk_fma_f32 v[6:7], v[146:147], v[166:167], v[6:7]
	v_pk_fma_f32 v[8:9], v[148:149], v[168:169], v[8:9]
	v_pk_fma_f32 v[10:11], v[154:155], v[10:11], v[158:159]
	v_pk_fma_f32 v[12:13], v[156:157], v[12:13], v[160:161]
	v_pk_fma_f32 v[10:11], v[150:151], v[166:167], v[10:11]
	v_pk_fma_f32 v[12:13], v[152:153], v[168:169], v[12:13]
	v_pk_fma_f32 v[10:11], v[146:147], v[162:163], v[10:11]
	v_pk_fma_f32 v[12:13], v[148:149], v[164:165], v[12:13]
	v_pk_mul_f32 v[30:31], v[10:11], s[100:101]
	v_pk_mul_f32 v[32:33], v[12:13], s[100:101]
	v_pk_mul_f32 v[54:55], v[6:7], s[100:101]
	v_pk_mul_f32 v[56:57], v[8:9], s[100:101]
	v_exp_f32_e32 v30, v30
	v_exp_f32_e32 v31, v31
	v_exp_f32_e32 v32, v32
	v_exp_f32_e32 v33, v33
	v_exp_f32_e32 v54, v54
	v_exp_f32_e32 v55, v55
	v_exp_f32_e32 v56, v56
	v_exp_f32_e32 v57, v57
	v_pk_add_f32 v[30:31], v[30:31], s[98:99]
	v_pk_add_f32 v[32:33], v[32:33], s[98:99]
	v_pk_add_f32 v[54:55], v[54:55], s[98:99]
	v_pk_add_f32 v[56:57], v[56:57], s[98:99]
	v_rcp_f32_e32 v30, v30
	v_rcp_f32_e32 v31, v31
	v_rcp_f32_e32 v32, v32
	v_rcp_f32_e32 v33, v33
	v_rcp_f32_e32 v54, v54
	v_rcp_f32_e32 v55, v55
	v_rcp_f32_e32 v56, v56
	v_rcp_f32_e32 v57, v57
	v_pk_mul_f32 v[10:11], v[10:11], v[22:23]
	v_pk_mul_f32 v[12:13], v[12:13], v[24:25]
	v_pk_mul_f32 v[6:7], v[6:7], v[18:19]
	v_pk_mul_f32 v[8:9], v[8:9], v[20:21]
	v_pk_mul_f32 v[10:11], v[10:11], v[30:31]
	v_pk_mul_f32 v[12:13], v[12:13], v[32:33]
	v_pk_mul_f32 v[6:7], v[6:7], v[54:55]
	v_pk_mul_f32 v[8:9], v[8:9], v[56:57]
	v_pk_mul_f32 v[30:31], v[2:3], s[100:101]
	v_pk_mul_f32 v[32:33], v[4:5], s[100:101]
	v_pk_mul_f32 v[54:55], v[26:27], s[100:101]
	v_pk_mul_f32 v[56:57], v[28:29], s[100:101]
	v_exp_f32_e32 v30, v30
	v_exp_f32_e32 v31, v31
	v_exp_f32_e32 v32, v32
	v_exp_f32_e32 v33, v33
	v_exp_f32_e32 v54, v54
	v_exp_f32_e32 v55, v55
	v_exp_f32_e32 v56, v56
	v_exp_f32_e32 v57, v57
	v_pk_add_f32 v[30:31], v[30:31], s[98:99]
	v_pk_add_f32 v[32:33], v[32:33], s[98:99]
	v_pk_add_f32 v[54:55], v[54:55], s[98:99]
	v_pk_add_f32 v[56:57], v[56:57], s[98:99]
	v_rcp_f32_e32 v30, v30
	v_rcp_f32_e32 v31, v31
	v_rcp_f32_e32 v32, v32
	v_rcp_f32_e32 v33, v33
	v_rcp_f32_e32 v54, v54
	v_rcp_f32_e32 v55, v55
	v_rcp_f32_e32 v56, v56
	v_rcp_f32_e32 v57, v57
	v_pk_mul_f32 v[2:3], v[2:3], v[14:15]
	v_pk_mul_f32 v[4:5], v[4:5], v[16:17]
	v_pk_mul_f32 v[26:27], v[26:27], v[58:59]
	v_pk_mul_f32 v[28:29], v[28:29], v[60:61]
	v_pk_mul_f32 v[2:3], v[2:3], v[30:31]
	v_pk_mul_f32 v[4:5], v[4:5], v[32:33]
	v_pk_mul_f32 v[26:27], v[26:27], v[54:55]
	v_pk_mul_f32 v[28:29], v[28:29], v[56:57]
	v_add_u32_e32 v244, 0xb0000, v244
	v_cvt_pk_bf16_f32 v110, v94, v95
	v_cvt_pk_bf16_f32 v111, v96, v97
	v_cvt_pk_bf16_f32 v112, v10, v11
	v_cvt_pk_bf16_f32 v113, v12, v13
	global_store_dwordx4 v244, v[110:113], s[52:53]
	v_add_u32_e32 v244, 0x1600, v244
	v_cvt_pk_bf16_f32 v22, v90, v91
	v_cvt_pk_bf16_f32 v23, v92, v93
	v_cvt_pk_bf16_f32 v24, v6, v7
	v_cvt_pk_bf16_f32 v25, v8, v9
	global_store_dwordx4 v244, v[22:25], s[52:53]
	v_add_u32_e32 v244, 0x1600, v244
	v_cvt_pk_bf16_f32 v110, v86, v87
	v_cvt_pk_bf16_f32 v111, v88, v89
	v_cvt_pk_bf16_f32 v112, v2, v3
	v_cvt_pk_bf16_f32 v113, v4, v5
	global_store_dwordx4 v244, v[110:113], s[52:53]
	v_add_u32_e32 v244, 0x1600, v244
	v_cvt_pk_bf16_f32 v22, v114, v115
	v_cvt_pk_bf16_f32 v23, v116, v117
	v_cvt_pk_bf16_f32 v24, v26, v27
	v_cvt_pk_bf16_f32 v25, v28, v29
	global_store_dwordx4 v244, v[22:25], s[52:53]
	s_cmp_lg_u32 s54, 1
	s_cselect_b64 s[8:9], -1, 0
	s_andn2_b64 vcc, exec, s[4:5]
	s_mov_b64 s[4:5], -1
	s_cbranch_vccnz .LBB0_1313
	s_andn2_b64 vcc, exec, s[20:21]
	s_mov_b32 s43, s44
	s_mov_b64 s[30:31], s[16:17]
	s_mov_b64 s[4:5], s[40:41]
	s_cbranch_vccnz .LBB0_1350
	s_ashr_i32 s4, s44, 5
	s_mul_hi_i32 s5, s4, 0x5800
	s_mulk_i32 s4, 0x5800
	s_add_u32 s30, s3, s4
	s_addc_u32 s31, s6, s5
	s_mov_b32 s43, s42
	s_mov_b64 s[4:5], s[14:15]
